# grid barrier: non-leader workgroups poll the cross-XCD generation word (TOPGEN) directly instead of waiting for their XCD leader's relay through XGEN (one fewer hop on release); each still does its ow
# speedup vs baseline: 1.0076x; 1.0023x over previous
.LBB0_76:
	s_or_b64 exec, exec, s[8:9]
	v_cvt_f32_u32_e32 v6, v4
	s_waitcnt vmcnt(0)
	v_readfirstlane_b32 s3, v5
	v_sub_u32_e32 v5, 0, v4
	v_rcp_iflag_f32_e32 v6, v6
	v_add_u32_e32 v7, s3, v3
	v_mul_f32_e32 v6, 0x4f7ffffe, v6
	v_cvt_u32_f32_e32 v6, v6
	v_mul_lo_u32 v3, v5, v6
	v_mul_hi_u32 v3, v6, v3
	v_add_u32_e32 v3, v6, v3
	v_mul_hi_u32 v3, v7, v3
	v_mul_lo_u32 v5, v3, v4
	v_sub_u32_e32 v5, v7, v5
	v_add_u32_e32 v6, 1, v3
	v_cmp_ge_u32_e32 vcc, v5, v4
	s_nop 1
	v_cndmask_b32_e32 v3, v3, v6, vcc
	v_sub_u32_e32 v6, v5, v4
	v_cndmask_b32_e32 v5, v5, v6, vcc
	v_add_u32_e32 v6, 1, v3
	v_cmp_ge_u32_e32 vcc, v5, v4
	v_add_u32_e32 v5, 1, v7
	s_nop 0
	v_cndmask_b32_e32 v3, v3, v6, vcc
	v_mul_lo_u32 v6, v4, v3
	v_add_u32_e32 v4, v6, v4
	v_cmp_ne_u32_e32 vcc, v5, v4
	s_and_saveexec_b64 s[6:7], vcc
	s_xor_b64 s[6:7], exec, s[6:7]
	s_cbranch_execz .LBB0_90
	s_waitcnt lgkmcnt(0)
	v_mov_b32_e32 v2, 0x7000
	global_load_dword v2, v2, s[34:35] offset:1280 sc1
	s_add_u32 s12, s34, 0x7500
	s_addc_u32 s13, s35, 0
	s_waitcnt vmcnt(0)
	v_cmp_eq_u32_e32 vcc, v2, v3
	s_and_saveexec_b64 s[8:9], vcc
	s_cbranch_execz .LBB0_89
	s_add_u32 s10, s34, 0x4200
	s_addc_u32 s11, s35, 0
	s_mov_b32 s3, 1
	s_mov_b64 s[16:17], 0
	v_mov_b32_e32 v2, 0
	s_branch .LBB0_80

.LBB0_280:
	s_or_b64 exec, exec, s[10:11]
	v_cvt_f32_u32_e32 v6, v4
	s_waitcnt vmcnt(0)
	v_readfirstlane_b32 s6, v5
	v_sub_u32_e32 v5, 0, v4
	v_rcp_iflag_f32_e32 v6, v6
	v_add_u32_e32 v7, s6, v3
	v_mul_f32_e32 v6, 0x4f7ffffe, v6
	v_cvt_u32_f32_e32 v6, v6
	v_mul_lo_u32 v3, v5, v6
	v_mul_hi_u32 v3, v6, v3
	v_add_u32_e32 v3, v6, v3
	v_mul_hi_u32 v3, v7, v3
	v_mul_lo_u32 v5, v3, v4
	v_sub_u32_e32 v5, v7, v5
	v_add_u32_e32 v6, 1, v3
	v_cmp_ge_u32_e32 vcc, v5, v4
	s_nop 1
	v_cndmask_b32_e32 v3, v3, v6, vcc
	v_sub_u32_e32 v6, v5, v4
	v_cndmask_b32_e32 v5, v5, v6, vcc
	v_add_u32_e32 v6, 1, v3
	v_cmp_ge_u32_e32 vcc, v5, v4
	v_add_u32_e32 v5, 1, v7
	s_nop 0
	v_cndmask_b32_e32 v3, v3, v6, vcc
	v_mul_lo_u32 v6, v4, v3
	v_add_u32_e32 v4, v6, v4
	v_cmp_ne_u32_e32 vcc, v5, v4
	s_and_saveexec_b64 s[6:7], vcc
	s_xor_b64 s[6:7], exec, s[6:7]
	s_cbranch_execz .LBB0_294
	s_waitcnt lgkmcnt(0)
	v_mov_b32_e32 v2, 0x7000
	global_load_dword v2, v2, s[34:35] offset:1280 sc1
	s_add_u32 s16, s34, 0x7500
	s_addc_u32 s17, s35, 0
	s_waitcnt vmcnt(0)
	v_cmp_eq_u32_e32 vcc, v2, v3
	s_and_saveexec_b64 s[10:11], vcc
	s_cbranch_execz .LBB0_293
	s_add_u32 s12, s34, 0x4200
	s_addc_u32 s13, s35, 0
	s_mov_b32 s26, 1
	s_mov_b64 s[18:19], 0
	v_mov_b32_e32 v2, 0
	s_branch .LBB0_284

.LBB0_459:
	s_or_b64 exec, exec, s[8:9]
	v_cvt_f32_u32_e32 v5, v3
	s_waitcnt vmcnt(0)
	v_readfirstlane_b32 s6, v4
	v_sub_u32_e32 v4, 0, v3
	v_rcp_iflag_f32_e32 v5, v5
	v_add_u32_e32 v6, s6, v2
	v_mul_f32_e32 v5, 0x4f7ffffe, v5
	v_cvt_u32_f32_e32 v5, v5
	v_mul_lo_u32 v2, v4, v5
	v_mul_hi_u32 v2, v5, v2
	v_add_u32_e32 v2, v5, v2
	v_mul_hi_u32 v2, v6, v2
	v_mul_lo_u32 v4, v2, v3
	v_sub_u32_e32 v4, v6, v4
	v_add_u32_e32 v5, 1, v2
	v_cmp_ge_u32_e32 vcc, v4, v3
	s_nop 1
	v_cndmask_b32_e32 v2, v2, v5, vcc
	v_sub_u32_e32 v5, v4, v3
	v_cndmask_b32_e32 v4, v4, v5, vcc
	v_add_u32_e32 v5, 1, v2
	v_cmp_ge_u32_e32 vcc, v4, v3
	v_add_u32_e32 v4, 1, v6
	s_nop 0
	v_cndmask_b32_e32 v2, v2, v5, vcc
	v_mul_lo_u32 v5, v3, v2
	v_add_u32_e32 v3, v5, v3
	v_cmp_ne_u32_e32 vcc, v4, v3
	s_and_saveexec_b64 s[6:7], vcc
	s_xor_b64 s[6:7], exec, s[6:7]
	s_cbranch_execz .LBB0_473
	s_waitcnt lgkmcnt(0)
	v_mov_b32_e32 v1, 0x7000
	global_load_dword v1, v1, s[34:35] offset:1280 sc1
	s_add_u32 s12, s34, 0x7500
	s_addc_u32 s13, s35, 0
	s_waitcnt vmcnt(0)
	v_cmp_eq_u32_e32 vcc, v1, v2
	s_and_saveexec_b64 s[8:9], vcc
	s_cbranch_execz .LBB0_472
	s_add_u32 s10, s34, 0x4200
	s_addc_u32 s11, s35, 0
	s_mov_b32 s26, 1
	s_mov_b64 s[16:17], 0
	v_mov_b32_e32 v1, 0
	s_branch .LBB0_463

.LBB0_514:
	s_or_b64 exec, exec, s[8:9]
	v_cvt_f32_u32_e32 v6, v4
	s_waitcnt vmcnt(0)
	v_readfirstlane_b32 s6, v5
	v_sub_u32_e32 v5, 0, v4
	v_rcp_iflag_f32_e32 v6, v6
	v_add_u32_e32 v7, s6, v3
	v_mul_f32_e32 v6, 0x4f7ffffe, v6
	v_cvt_u32_f32_e32 v6, v6
	v_mul_lo_u32 v3, v5, v6
	v_mul_hi_u32 v3, v6, v3
	v_add_u32_e32 v3, v6, v3
	v_mul_hi_u32 v3, v7, v3
	v_mul_lo_u32 v5, v3, v4
	v_sub_u32_e32 v5, v7, v5
	v_add_u32_e32 v6, 1, v3
	v_cmp_ge_u32_e32 vcc, v5, v4
	s_nop 1
	v_cndmask_b32_e32 v3, v3, v6, vcc
	v_sub_u32_e32 v6, v5, v4
	v_cndmask_b32_e32 v5, v5, v6, vcc
	v_add_u32_e32 v6, 1, v3
	v_cmp_ge_u32_e32 vcc, v5, v4
	v_add_u32_e32 v5, 1, v7
	s_nop 0
	v_cndmask_b32_e32 v3, v3, v6, vcc
	v_mul_lo_u32 v6, v4, v3
	v_add_u32_e32 v4, v6, v4
	v_cmp_ne_u32_e32 vcc, v5, v4
	s_and_saveexec_b64 s[6:7], vcc
	s_xor_b64 s[6:7], exec, s[6:7]
	s_cbranch_execz .LBB0_528
	s_waitcnt lgkmcnt(0)
	v_mov_b32_e32 v2, 0x7000
	global_load_dword v2, v2, s[34:35] offset:1280 sc1
	s_add_u32 s12, s34, 0x7500
	s_addc_u32 s13, s35, 0
	s_waitcnt vmcnt(0)
	v_cmp_eq_u32_e32 vcc, v2, v3
	s_and_saveexec_b64 s[8:9], vcc
	s_cbranch_execz .LBB0_527
	s_add_u32 s10, s34, 0x4200
	s_addc_u32 s11, s35, 0
	s_mov_b32 s26, 1
	s_mov_b64 s[16:17], 0
	v_mov_b32_e32 v2, 0
	s_branch .LBB0_518

.LBB0_669:
	s_or_b64 exec, exec, s[8:9]
	v_cvt_f32_u32_e32 v6, v4
	s_waitcnt vmcnt(0)
	v_readfirstlane_b32 s6, v5
	v_sub_u32_e32 v5, 0, v4
	v_rcp_iflag_f32_e32 v6, v6
	v_add_u32_e32 v7, s6, v3
	v_mul_f32_e32 v6, 0x4f7ffffe, v6
	v_cvt_u32_f32_e32 v6, v6
	v_mul_lo_u32 v3, v5, v6
	v_mul_hi_u32 v3, v6, v3
	v_add_u32_e32 v3, v6, v3
	v_mul_hi_u32 v3, v7, v3
	v_mul_lo_u32 v5, v3, v4
	v_sub_u32_e32 v5, v7, v5
	v_add_u32_e32 v6, 1, v3
	v_cmp_ge_u32_e32 vcc, v5, v4
	s_nop 1
	v_cndmask_b32_e32 v3, v3, v6, vcc
	v_sub_u32_e32 v6, v5, v4
	v_cndmask_b32_e32 v5, v5, v6, vcc
	v_add_u32_e32 v6, 1, v3
	v_cmp_ge_u32_e32 vcc, v5, v4
	v_add_u32_e32 v5, 1, v7
	s_nop 0
	v_cndmask_b32_e32 v3, v3, v6, vcc
	v_mul_lo_u32 v6, v4, v3
	v_add_u32_e32 v4, v6, v4
	v_cmp_ne_u32_e32 vcc, v5, v4
	s_and_saveexec_b64 s[6:7], vcc
	s_xor_b64 s[6:7], exec, s[6:7]
	s_cbranch_execz .LBB0_683
	s_waitcnt lgkmcnt(0)
	v_mov_b32_e32 v2, 0x7000
	global_load_dword v2, v2, s[34:35] offset:1280 sc1
	s_add_u32 s16, s34, 0x7500
	s_addc_u32 s17, s35, 0
	s_waitcnt vmcnt(0)
	v_cmp_eq_u32_e32 vcc, v2, v3
	s_and_saveexec_b64 s[8:9], vcc
	s_cbranch_execz .LBB0_682
	s_add_u32 s10, s34, 0x4200
	s_addc_u32 s11, s35, 0
	s_mov_b32 s26, 1
	s_mov_b64 s[18:19], 0
	v_mov_b32_e32 v2, 0
	s_branch .LBB0_673

.LBB0_955:
	s_or_b64 exec, exec, s[10:11]
	v_cvt_f32_u32_e32 v6, v4
	s_waitcnt vmcnt(0)
	v_readfirstlane_b32 s8, v5
	v_sub_u32_e32 v5, 0, v4
	v_rcp_iflag_f32_e32 v6, v6
	v_add_u32_e32 v7, s8, v3
	v_mul_f32_e32 v6, 0x4f7ffffe, v6
	v_cvt_u32_f32_e32 v6, v6
	v_mul_lo_u32 v3, v5, v6
	v_mul_hi_u32 v3, v6, v3
	v_add_u32_e32 v3, v6, v3
	v_mul_hi_u32 v3, v7, v3
	v_mul_lo_u32 v5, v3, v4
	v_sub_u32_e32 v5, v7, v5
	v_add_u32_e32 v6, 1, v3
	v_cmp_ge_u32_e32 vcc, v5, v4
	s_nop 1
	v_cndmask_b32_e32 v3, v3, v6, vcc
	v_sub_u32_e32 v6, v5, v4
	v_cndmask_b32_e32 v5, v5, v6, vcc
	v_add_u32_e32 v6, 1, v3
	v_cmp_ge_u32_e32 vcc, v5, v4
	v_add_u32_e32 v5, 1, v7
	s_nop 0
	v_cndmask_b32_e32 v3, v3, v6, vcc
	v_mul_lo_u32 v6, v4, v3
	v_add_u32_e32 v4, v6, v4
	v_cmp_ne_u32_e32 vcc, v5, v4
	s_and_saveexec_b64 s[8:9], vcc
	s_xor_b64 s[8:9], exec, s[8:9]
	s_cbranch_execz .LBB0_969
	s_waitcnt lgkmcnt(0)
	v_mov_b32_e32 v2, 0x7000
	global_load_dword v2, v2, s[34:35] offset:1280 sc1
	s_add_u32 s16, s34, 0x7500
	s_addc_u32 s17, s35, 0
	s_waitcnt vmcnt(0)
	v_cmp_eq_u32_e32 vcc, v2, v3
	s_and_saveexec_b64 s[10:11], vcc
	s_cbranch_execz .LBB0_968
	s_add_u32 s12, s34, 0x4200
	s_addc_u32 s13, s35, 0
	s_mov_b32 s26, 1
	s_mov_b64 s[18:19], 0
	v_mov_b32_e32 v2, 0
	s_branch .LBB0_959

.LBB0_1052:
	s_or_b64 exec, exec, s[12:13]
	v_cvt_f32_u32_e32 v6, v4
	s_waitcnt vmcnt(0)
	v_readfirstlane_b32 s10, v5
	v_sub_u32_e32 v5, 0, v4
	v_rcp_iflag_f32_e32 v6, v6
	v_add_u32_e32 v7, s10, v3
	v_mul_f32_e32 v6, 0x4f7ffffe, v6
	v_cvt_u32_f32_e32 v6, v6
	v_mul_lo_u32 v3, v5, v6
	v_mul_hi_u32 v3, v6, v3
	v_add_u32_e32 v3, v6, v3
	v_mul_hi_u32 v3, v7, v3
	v_mul_lo_u32 v5, v3, v4
	v_sub_u32_e32 v5, v7, v5
	v_add_u32_e32 v6, 1, v3
	v_cmp_ge_u32_e32 vcc, v5, v4
	s_nop 1
	v_cndmask_b32_e32 v3, v3, v6, vcc
	v_sub_u32_e32 v6, v5, v4
	v_cndmask_b32_e32 v5, v5, v6, vcc
	v_add_u32_e32 v6, 1, v3
	v_cmp_ge_u32_e32 vcc, v5, v4
	v_add_u32_e32 v5, 1, v7
	s_nop 0
	v_cndmask_b32_e32 v3, v3, v6, vcc
	v_mul_lo_u32 v6, v4, v3
	v_add_u32_e32 v4, v6, v4
	v_cmp_ne_u32_e32 vcc, v5, v4
	s_and_saveexec_b64 s[10:11], vcc
	s_xor_b64 s[10:11], exec, s[10:11]
	s_cbranch_execz .LBB0_1066
	s_waitcnt lgkmcnt(0)
	v_mov_b32_e32 v2, 0x7000
	global_load_dword v2, v2, s[34:35] offset:1280 sc1
	s_add_u32 s18, s34, 0x7500
	s_addc_u32 s19, s35, 0
	s_waitcnt vmcnt(0)
	v_cmp_eq_u32_e32 vcc, v2, v3
	s_and_saveexec_b64 s[12:13], vcc
	s_cbranch_execz .LBB0_1065
	s_add_u32 s16, s34, 0x4200
	s_addc_u32 s17, s35, 0
	s_mov_b32 s30, 1
	s_mov_b64 s[20:21], 0
	v_mov_b32_e32 v2, 0
	s_branch .LBB0_1056

.LBB0_1289:
	s_or_b64 exec, exec, s[18:19]
	v_cvt_f32_u32_e32 v6, v4
	s_waitcnt vmcnt(0)
	v_readfirstlane_b32 s16, v5
	v_sub_u32_e32 v5, 0, v4
	v_rcp_iflag_f32_e32 v6, v6
	v_add_u32_e32 v7, s16, v3
	v_mul_f32_e32 v6, 0x4f7ffffe, v6
	v_cvt_u32_f32_e32 v6, v6
	v_mul_lo_u32 v3, v5, v6
	v_mul_hi_u32 v3, v6, v3
	v_add_u32_e32 v3, v6, v3
	v_mul_hi_u32 v3, v7, v3
	v_mul_lo_u32 v5, v3, v4
	v_sub_u32_e32 v5, v7, v5
	v_add_u32_e32 v6, 1, v3
	v_cmp_ge_u32_e32 vcc, v5, v4
	s_nop 1
	v_cndmask_b32_e32 v3, v3, v6, vcc
	v_sub_u32_e32 v6, v5, v4
	v_cndmask_b32_e32 v5, v5, v6, vcc
	v_add_u32_e32 v6, 1, v3
	v_cmp_ge_u32_e32 vcc, v5, v4
	v_add_u32_e32 v5, 1, v7
	s_nop 0
	v_cndmask_b32_e32 v3, v3, v6, vcc
	v_mul_lo_u32 v6, v4, v3
	v_add_u32_e32 v4, v6, v4
	v_cmp_ne_u32_e32 vcc, v5, v4
	s_and_saveexec_b64 s[16:17], vcc
	s_xor_b64 s[16:17], exec, s[16:17]
	s_cbranch_execz .LBB0_1303
	s_waitcnt lgkmcnt(0)
	v_mov_b32_e32 v2, 0x7000
	global_load_dword v2, v2, s[34:35] offset:1280 sc1
	s_add_u32 s22, s34, 0x7500
	s_addc_u32 s23, s35, 0
	s_waitcnt vmcnt(0)
	v_cmp_eq_u32_e32 vcc, v2, v3
	s_and_saveexec_b64 s[18:19], vcc
	s_cbranch_execz .LBB0_1302
	s_add_u32 s20, s34, 0x4200
	s_addc_u32 s21, s35, 0
	s_mov_b32 s33, 1
	s_mov_b64 s[24:25], 0
	v_mov_b32_e32 v2, 0
	s_branch .LBB0_1293

.LBB0_1395:
	s_or_b64 exec, exec, s[10:11]
	v_cvt_f32_u32_e32 v6, v4
	s_waitcnt vmcnt(0)
	v_readfirstlane_b32 s8, v5
	v_sub_u32_e32 v5, 0, v4
	v_rcp_iflag_f32_e32 v6, v6
	v_add_u32_e32 v7, s8, v3
	v_mul_f32_e32 v6, 0x4f7ffffe, v6
	v_cvt_u32_f32_e32 v6, v6
	v_mul_lo_u32 v3, v5, v6
	v_mul_hi_u32 v3, v6, v3
	v_add_u32_e32 v3, v6, v3
	v_mul_hi_u32 v3, v7, v3
	v_mul_lo_u32 v5, v3, v4
	v_sub_u32_e32 v5, v7, v5
	v_add_u32_e32 v6, 1, v3
	v_cmp_ge_u32_e32 vcc, v5, v4
	s_nop 1
	v_cndmask_b32_e32 v3, v3, v6, vcc
	v_sub_u32_e32 v6, v5, v4
	v_cndmask_b32_e32 v5, v5, v6, vcc
	v_add_u32_e32 v6, 1, v3
	v_cmp_ge_u32_e32 vcc, v5, v4
	v_add_u32_e32 v5, 1, v7
	s_nop 0
	v_cndmask_b32_e32 v3, v3, v6, vcc
	v_mul_lo_u32 v6, v4, v3
	v_add_u32_e32 v4, v6, v4
	v_cmp_ne_u32_e32 vcc, v5, v4
	s_and_saveexec_b64 s[8:9], vcc
	s_xor_b64 s[8:9], exec, s[8:9]
	s_cbranch_execz .LBB0_1409
	s_waitcnt lgkmcnt(0)
	v_mov_b32_e32 v2, 0x7000
	global_load_dword v2, v2, s[34:35] offset:1280 sc1
	s_add_u32 s16, s34, 0x7500
	s_addc_u32 s17, s35, 0
	s_waitcnt vmcnt(0)
	v_cmp_eq_u32_e32 vcc, v2, v3
	s_and_saveexec_b64 s[10:11], vcc
	s_cbranch_execz .LBB0_1408
	s_add_u32 s12, s34, 0x4200
	s_addc_u32 s13, s35, 0
	s_mov_b32 s28, 1
	s_mov_b64 s[18:19], 0
	v_mov_b32_e32 v2, 0
	s_branch .LBB0_1399

.LBB0_1618:
	s_or_b64 exec, exec, s[10:11]
	v_cvt_f32_u32_e32 v6, v4
	s_waitcnt vmcnt(0)
	v_readfirstlane_b32 s8, v5
	v_sub_u32_e32 v5, 0, v4
	v_rcp_iflag_f32_e32 v6, v6
	v_add_u32_e32 v7, s8, v3
	v_mul_f32_e32 v6, 0x4f7ffffe, v6
	v_cvt_u32_f32_e32 v6, v6
	v_mul_lo_u32 v3, v5, v6
	v_mul_hi_u32 v3, v6, v3
	v_add_u32_e32 v3, v6, v3
	v_mul_hi_u32 v3, v7, v3
	v_mul_lo_u32 v5, v3, v4
	v_sub_u32_e32 v5, v7, v5
	v_add_u32_e32 v6, 1, v3
	v_cmp_ge_u32_e32 vcc, v5, v4
	s_nop 1
	v_cndmask_b32_e32 v3, v3, v6, vcc
	v_sub_u32_e32 v6, v5, v4
	v_cndmask_b32_e32 v5, v5, v6, vcc
	v_add_u32_e32 v6, 1, v3
	v_cmp_ge_u32_e32 vcc, v5, v4
	v_add_u32_e32 v5, 1, v7
	s_nop 0
	v_cndmask_b32_e32 v3, v3, v6, vcc
	v_mul_lo_u32 v6, v4, v3
	v_add_u32_e32 v4, v6, v4
	v_cmp_ne_u32_e32 vcc, v5, v4
	s_and_saveexec_b64 s[8:9], vcc
	s_xor_b64 s[8:9], exec, s[8:9]
	s_cbranch_execz .LBB0_1632
	s_waitcnt lgkmcnt(0)
	v_mov_b32_e32 v2, 0x7000
	global_load_dword v2, v2, s[34:35] offset:1280 sc1
	s_add_u32 s14, s34, 0x7500
	s_addc_u32 s15, s35, 0
	s_waitcnt vmcnt(0)
	v_cmp_eq_u32_e32 vcc, v2, v3
	s_and_saveexec_b64 s[10:11], vcc
	s_cbranch_execz .LBB0_1631
	s_add_u32 s12, s34, 0x4200
	s_addc_u32 s13, s35, 0
	s_mov_b32 s26, 1
	s_mov_b64 s[16:17], 0
	v_mov_b32_e32 v2, 0
	s_branch .LBB0_1622
